# scan S-update: decay factors read once per wave (one ds_read_b64) and applied with DPP row broadcasts instead of 8 ds_read_b128
# speedup vs baseline: 1.0020x; 1.0020x over previous
; __device__ __forceinline__ int tid_of(int wave_id) { int t = wave_id * 64 + lane_id(); asm volatile("" : "+v"(t)); return t; }
; #define ATT_BAR() do { asm volatile("s_waitcnt lgkmcnt(0)" ::: "memory"); __builtin_amdgcn_s_barrier(); asm volatile("" ::: "memory"); } while (0)
; __device__ __forceinline__ void hgrn_scan(const Params& p, LAS unsigned char* lds, int chain) {
;     int tid_o = tid_of(p.wave_id);
;     const int tid = tid_o, lane = tid & 63, wave = __builtin_amdgcn_readfirstlane(tid >> 6);
;     const int li = lane & 15, g = lane >> 4, qq = li >> 2, pp = li & 3;
;     const int dir = chain / (BATCH * NHEAD), b = (chain / NHEAD) % BATCH, h = chain % NHEAD;
;     const bf16* IA = (const bf16*)(p.ws + WS_IA) + h * HD;
;     bf16* O = (bf16*)(p.ws + (dir == 0 ? WS_OF2 : WS_OB2)) + h * HD + 16 * wave + 4 * g;
;     const long ost = dir ? -(long)WA : (long)WA;
;     const unsigned char* img0 = p.ws + WS_HIMG + (size_t)chain * NCH * HIMG_BYTES;
;     f32x4 S[8];
; #pragma unroll
;     for (int i = 0; i < 8; ++i) S[i] = (f32x4){0.f, 0.f, 0.f, 0.f};
;     u32x4 rq[2][2], rk[2][2], rp[2], rd[2], rv[2][2];
;     ...
;     HS_LOAD(0, 0); HS_LOAD(1, 1);
;     HS_STORE(0, 0);
;     HS_LOAD(2, 0);
;     ATT_BAR();
.LBB0_405:
	s_or_b64 exec, exec, s[12:13]
	s_movk_i32 s12, 0x120
	v_mul_lo_u32 v46, v132, s12
	s_mov_b32 s18, 0x6542000
	s_and_b64 s[12:13], s[6:7], exec
	s_cselect_b32 s12, s18, 0x8942000
	s_add_u32 s12, s26, s12
	s_addc_u32 s21, s27, 0
	s_ashr_i32 s18, s20, 2
	s_and_b32 s18, s18, -16
	s_ashr_i32 s19, s18, 31
	s_lshl_b64 s[38:39], s[16:17], 4
	s_add_u32 s12, s12, s38
	v_lshrrev_b32_e32 v32, 2, v47
	s_addc_u32 s20, s21, s39
	s_lshl_b64 s[16:17], s[18:19], 5
	v_and_b32_e32 v52, 12, v32
	s_add_u32 s16, s12, s16
	v_mov_b32_e32 v115, 0
	s_addc_u32 s17, s20, s17
	v_lshlrev_b32_e32 v116, 1, v52
	v_mov_b32_e32 v117, v115
	s_movk_i32 s12, 0x80
	s_and_b64 s[38:39], s[6:7], exec
	s_cselect_b32 s38, 0, 0x7800
	s_sub_u32 s16, s16, s38
	s_subb_u32 s17, s17, 0
	v_and_b32_e32 v237, 15, v47
	v_sub_u32_e32 v238, 15, v237
	v_cndmask_b32_e64 v238, v238, v237, s[6:7]
	v_lshl_add_u32 v238, v238, 5, v116
	v_mov_b32_e32 v239, 0
	v_lshl_add_u64 v[44:45], s[16:17], 0, v[238:239]
	v_mov_b32_e32 v117, 0x8ff
	v_mov_b32_e32 v138, 0xff
	v_cmp_gt_i32_e32 vcc, s12, v132
	v_add_u32_e32 v34, 0x80, v132
	v_add_u32_e32 v32, 0xffffff80, v132
	v_cndmask_b32_e32 v35, v117, v138, vcc
	v_cndmask_b32_e32 v36, v32, v34, vcc
	v_mov_b32_e32 v32, s11
	v_sub_u32_e32 v34, v35, v34
	v_cndmask_b32_e64 v33, v32, 0, vcc
	v_mov_b32_e32 v32, s10
	v_mov_b32_e32 v37, s3
	v_cndmask_b32_e64 v34, v34, v36, s[6:7]
	v_cndmask_b32_e32 v32, v32, v37, vcc
	v_ashrrev_i32_e32 v35, 31, v34
	v_lshl_add_u64 v[32:33], v[32:33], 0, v[34:35]
	v_lshlrev_b64 v[32:33], 11, v[32:33]
	v_lshl_add_u64 v[32:33], s[8:9], 0, v[32:33]
	v_lshl_add_u64 v[50:51], v[32:33], 0, v[114:115]
	global_load_dwordx4 v[32:35], v[50:51], off offset:16
	global_load_dwordx4 v[36:39], v[50:51], off
	s_movk_i32 s16, 0xa0
	v_lshlrev_b32_e32 v50, 3, v47
	s_lshl_b32 s12, s18, 1
	v_mul_lo_u32 v51, v132, s16
	s_movk_i32 s16, 0x90
	s_lshl_b64 s[14:15], s[14:15], 22
	v_and_b32_e32 v49, 15, v47
	v_lshrrev_b32_e32 v235, 1, v49
	v_lshlrev_b32_e32 v235, 6, v235
	v_and_b32_e32 v240, 1, v49
	v_lshl_add_u32 v235, v240, 3, v235
	v_lshl_add_u32 v235, v52, 2, v235
	v_and_b32_e32 v50, 24, v50
	v_mul_lo_u32 v53, v132, s16
	v_lshl_add_u64 v[118:119], v[44:45], 0, s[14:15]
	s_movk_i32 s16, 0x400
	s_and_b64 s[14:15], s[6:7], exec
	v_add_u32_e32 v139, 0, v50
	v_or_b32_e32 v56, 16, v49
	v_or_b32_e32 v57, 32, v49
	v_or_b32_e32 v58, 48, v49
	s_cselect_b32 s14, s16, 0xfffffc00
	s_add_i32 s17, 0, 0x1d400
	v_add_u32_e32 v54, s12, v139
	v_bfe_u32 v47, v47, 2, 4
	v_mov_b32_e32 v120, 0
	v_mov_b32_e32 v121, 0
	s_lshl_b32 s38, s14, 4
	s_ashr_i32 s39, s14, 31
	v_mov_b32_e32 v122, s38
	v_mov_b32_e32 v123, s39
	s_lshl_b32 s38, s14, 5
	v_mov_b32_e32 v124, s38
	v_mov_b32_e32 v125, s39
	s_mul_i32 s38, s14, 48
	v_mov_b32_e32 v126, s38
	v_mov_b32_e32 v127, s39
	s_add_i32 s14, 0, 0x10e00
	s_add_i32 s15, 0, 0x1ae00
	s_add_i32 s16, 0, 0x15e00
	s_add_i32 s12, s12, s17
	s_waitcnt lgkmcnt(0)
	s_barrier
	v_mul_u32_u24_e32 v55, 0x120, v47
	v_mul_u32_u24_e32 v141, 0xa0, v47
	v_add_u32_e32 v44, s14, v51
	v_add_u32_e32 v47, s16, v48
	v_add_u32_e32 v152, s17, v46
	v_add_u32_e32 v46, s12, v50
	v_add_u32_e32 v48, s14, v50
	v_add_u32_e32 v154, 0, v51
	v_lshlrev_b32_e32 v50, 4, v132
	s_add_u32 s14, s26, s23
	v_mul_u32_u24_e32 v142, 0x90, v49
	v_lshlrev_b32_e32 v143, 2, v52
	v_mul_u32_u24_e32 v144, 0x88, v49
	v_add_u32_e32 v45, s15, v53
	v_add_u32_e32 v49, s15, v116
	v_sub_u32_e32 v50, v154, v50
	s_addc_u32 s15, s27, s22
	s_mov_b32 s13, 0
	s_movk_i32 s20, 0x8ff
	v_add_u32_e32 v140, 0, v116
	v_or_b32_e32 v145, 64, v143
	v_or_b32_e32 v146, 0x80, v143
	v_or_b32_e32 v147, 0xc0, v143
	s_movk_i32 s21, 0x100
	v_or_b32_e32 v148, 0x100, v143
	v_or_b32_e32 v149, 0x140, v143
	v_or_b32_e32 v150, 0x180, v143
	v_or_b32_e32 v151, 0x1c0, v143
	v_add_u32_e32 v153, s16, v116
	v_mul_u32_u24_e32 v155, 0x88, v56
	v_sub_u32_e32 v156, 0, v132
	v_lshl_add_u64 v[128:129], s[14:15], 0, v[40:41]
	v_lshl_add_u64 v[130:131], s[14:15], 0, v[42:43]
	s_mov_b64 s[14:15], 0
	s_movk_i32 s22, 0xff00
	s_mov_b32 s30, -2
	v_add_u32_e32 v157, v54, v55
	v_add_u32_e32 v158, v44, v113
	v_add_u32_e32 v159, v45, v113
	v_add_u32_e32 v160, v47, v113
	v_add_u32_e32 v161, v46, v55
	v_add_u32_e32 v162, v48, v141
	v_add_u32_e32 v163, v49, v142
	v_add_u32_e32 v164, v50, v113
	v_mov_b32_e32 v68, v115
	v_mov_b32_e32 v69, v115
	v_mov_b32_e32 v70, v115
	v_mov_b32_e32 v71, v115
	v_mov_b32_e32 v64, v115
	v_mov_b32_e32 v65, v115
	v_mov_b32_e32 v66, v115
	v_mov_b32_e32 v67, v115
	v_mov_b32_e32 v84, v115
	v_mov_b32_e32 v85, v115
	v_mov_b32_e32 v86, v115
	v_mov_b32_e32 v87, v115
	v_mov_b32_e32 v72, v115
	v_mov_b32_e32 v73, v115
	v_mov_b32_e32 v74, v115
	v_mov_b32_e32 v75, v115
	v_mov_b32_e32 v88, v115
	v_mov_b32_e32 v89, v115
	v_mov_b32_e32 v90, v115
	v_mov_b32_e32 v91, v115
	v_mov_b32_e32 v80, v115
	v_mov_b32_e32 v81, v115
	v_mov_b32_e32 v82, v115
	v_mov_b32_e32 v83, v115
	v_mov_b32_e32 v92, v115
	v_mov_b32_e32 v93, v115
	v_mov_b32_e32 v94, v115
	v_mov_b32_e32 v95, v115
	v_mov_b32_e32 v76, v115
	v_mov_b32_e32 v77, v115
	v_mov_b32_e32 v78, v115
	v_mov_b32_e32 v79, v115
	s_branch .LBB0_408

; #define LAS __attribute__((address_space(3)))
; __device__ __forceinline__ void hgrn_scan(const Params& p, LAS unsigned char* lds, int chain) {
;     ...
; #pragma unroll
;         for (int blk = 0; blk < 8; ++blk) {
;             const f32x4 d4 = *(const LAS f32x4*)(bb + SB_D + (16 * blk + 4 * g) * 4);
;             f32x4 s = S[blk] * d4;
; #pragma unroll
;             for (int sp = 0; sp < 2; ++sp) {
;                 const LAS unsigned char* kp = bb + SB_KD + (16 * blk + li) * HPK + (32 * sp + 4 * g) * 2;
;                 s = __builtin_amdgcn_mfma_f32_16x16x32_bf16(cat8u(*(const LAS u32x2*)kp, *(const LAS u32x2*)(kp + 32)), vf[sp], s, 0, 0, 0);
;             }
;             S[blk] = s;
;         }
.LBB0_412:
	v_add_u32_e32 v165, v140, v144
	ds_read_b64 v[204:205], v235 offset:50176
	ds_read_b64 v[180:181], v165 offset:20480
	ds_read_b64 v[182:183], v165 offset:20512
	ds_read_b64 v[184:185], v165 offset:20544
	ds_read_b64 v[186:187], v165 offset:20576
	ds_read_b64 v[188:189], v165 offset:22656
	ds_read_b64 v[190:191], v165 offset:22688
	ds_read_b64 v[192:193], v165 offset:22720
	ds_read_b64 v[194:195], v165 offset:22752
	s_waitcnt lgkmcnt(8)
	ds_read_b64 v[196:197], v165 offset:24832
	ds_read_b64 v[198:199], v165 offset:24864
	ds_read_b64 v[200:201], v165 offset:24896
	ds_read_b64 v[202:203], v165 offset:24928
	s_waitcnt lgkmcnt(4)
	v_mul_f32_dpp v76, v204, v76 row_newbcast:0 row_mask:0xf bank_mask:0xf
	v_mul_f32_dpp v77, v205, v77 row_newbcast:0 row_mask:0xf bank_mask:0xf
	v_mul_f32_dpp v78, v204, v78 row_newbcast:1 row_mask:0xf bank_mask:0xf
	v_mul_f32_dpp v79, v205, v79 row_newbcast:1 row_mask:0xf bank_mask:0xf
	v_mul_f32_dpp v92, v204, v92 row_newbcast:2 row_mask:0xf bank_mask:0xf
	v_mul_f32_dpp v93, v205, v93 row_newbcast:2 row_mask:0xf bank_mask:0xf
	v_mul_f32_dpp v94, v204, v94 row_newbcast:3 row_mask:0xf bank_mask:0xf
	v_mul_f32_dpp v95, v205, v95 row_newbcast:3 row_mask:0xf bank_mask:0xf
	v_mfma_f32_16x16x32_bf16 v[76:79], v[180:183], v[100:103], v[76:79]
	s_nop 0
	v_mfma_f32_16x16x32_bf16 v[92:95], v[188:191], v[100:103], v[92:95]
	v_mfma_f32_16x16x32_bf16 v[76:79], v[184:187], v[96:99], v[76:79]
	v_mfma_f32_16x16x32_bf16 v[92:95], v[192:195], v[96:99], v[92:95]
	ds_read_b64 v[180:181], v165 offset:27008
	ds_read_b64 v[182:183], v165 offset:27040
	ds_read_b64 v[184:185], v165 offset:27072
	ds_read_b64 v[186:187], v165 offset:27104
	ds_read_b64 v[188:189], v165 offset:29184
	ds_read_b64 v[190:191], v165 offset:29216
	ds_read_b64 v[192:193], v165 offset:29248
	ds_read_b64 v[194:195], v165 offset:29280
	s_waitcnt lgkmcnt(4)
	v_mul_f32_dpp v80, v204, v80 row_newbcast:4 row_mask:0xf bank_mask:0xf
	v_mul_f32_dpp v81, v205, v81 row_newbcast:4 row_mask:0xf bank_mask:0xf
	v_mul_f32_dpp v82, v204, v82 row_newbcast:5 row_mask:0xf bank_mask:0xf
	v_mul_f32_dpp v83, v205, v83 row_newbcast:5 row_mask:0xf bank_mask:0xf
	v_mul_f32_dpp v88, v204, v88 row_newbcast:6 row_mask:0xf bank_mask:0xf
	v_mul_f32_dpp v89, v205, v89 row_newbcast:6 row_mask:0xf bank_mask:0xf
	v_mul_f32_dpp v90, v204, v90 row_newbcast:7 row_mask:0xf bank_mask:0xf
	v_mul_f32_dpp v91, v205, v91 row_newbcast:7 row_mask:0xf bank_mask:0xf
	v_mfma_f32_16x16x32_bf16 v[80:83], v[196:199], v[100:103], v[80:83]
	s_nop 0
	v_mfma_f32_16x16x32_bf16 v[88:91], v[180:183], v[100:103], v[88:91]
	v_mfma_f32_16x16x32_bf16 v[80:83], v[200:203], v[96:99], v[80:83]
	v_mfma_f32_16x16x32_bf16 v[88:91], v[184:187], v[96:99], v[88:91]
	ds_read_b64 v[196:197], v165 offset:31360
	ds_read_b64 v[198:199], v165 offset:31392
	ds_read_b64 v[200:201], v165 offset:31424
	ds_read_b64 v[202:203], v165 offset:31456
	ds_read_b64 v[180:181], v165 offset:33536
	ds_read_b64 v[182:183], v165 offset:33568
	ds_read_b64 v[184:185], v165 offset:33600
	ds_read_b64 v[186:187], v165 offset:33632
	s_waitcnt lgkmcnt(4)
	v_mul_f32_dpp v72, v204, v72 row_newbcast:8 row_mask:0xf bank_mask:0xf
	v_mul_f32_dpp v73, v205, v73 row_newbcast:8 row_mask:0xf bank_mask:0xf
	v_mul_f32_dpp v74, v204, v74 row_newbcast:9 row_mask:0xf bank_mask:0xf
	v_mul_f32_dpp v75, v205, v75 row_newbcast:9 row_mask:0xf bank_mask:0xf
	v_mul_f32_dpp v84, v204, v84 row_newbcast:10 row_mask:0xf bank_mask:0xf
	v_mul_f32_dpp v85, v205, v85 row_newbcast:10 row_mask:0xf bank_mask:0xf
	v_mul_f32_dpp v86, v204, v86 row_newbcast:11 row_mask:0xf bank_mask:0xf
	v_mul_f32_dpp v87, v205, v87 row_newbcast:11 row_mask:0xf bank_mask:0xf
	v_mfma_f32_16x16x32_bf16 v[72:75], v[188:191], v[100:103], v[72:75]
	s_nop 0
	v_mfma_f32_16x16x32_bf16 v[84:87], v[196:199], v[100:103], v[84:87]
	v_mfma_f32_16x16x32_bf16 v[72:75], v[192:195], v[96:99], v[72:75]
	v_mfma_f32_16x16x32_bf16 v[84:87], v[200:203], v[96:99], v[84:87]
	ds_read_b64 v[188:189], v165 offset:35712
	ds_read_b64 v[190:191], v165 offset:35744
	ds_read_b64 v[192:193], v165 offset:35776
	ds_read_b64 v[194:195], v165 offset:35808
	s_waitcnt lgkmcnt(0)
	v_mul_f32_dpp v64, v204, v64 row_newbcast:12 row_mask:0xf bank_mask:0xf
	v_mul_f32_dpp v65, v205, v65 row_newbcast:12 row_mask:0xf bank_mask:0xf
	v_mul_f32_dpp v66, v204, v66 row_newbcast:13 row_mask:0xf bank_mask:0xf
	v_mul_f32_dpp v67, v205, v67 row_newbcast:13 row_mask:0xf bank_mask:0xf
	v_mul_f32_dpp v68, v204, v68 row_newbcast:14 row_mask:0xf bank_mask:0xf
	v_mul_f32_dpp v69, v205, v69 row_newbcast:14 row_mask:0xf bank_mask:0xf
	v_mul_f32_dpp v70, v204, v70 row_newbcast:15 row_mask:0xf bank_mask:0xf
	v_mul_f32_dpp v71, v205, v71 row_newbcast:15 row_mask:0xf bank_mask:0xf
	v_mfma_f32_16x16x32_bf16 v[64:67], v[180:183], v[100:103], v[64:67]
	s_nop 0
	v_mfma_f32_16x16x32_bf16 v[68:71], v[188:191], v[100:103], v[68:71]
	v_mfma_f32_16x16x32_bf16 v[64:67], v[184:187], v[96:99], v[64:67]
	v_mfma_f32_16x16x32_bf16 v[68:71], v[192:195], v[96:99], v[68:71]
	s_cmp_lt_u32 s23, 3
	s_cbranch_scc1 .LBB0_414
	s_waitcnt vmcnt(6)
	ds_write_b128 v158, v[40:43]
	s_waitcnt vmcnt(5)
	ds_write_b128 v158, v[44:47] offset:10240
	s_waitcnt vmcnt(4)
	ds_write_b128 v159, v[56:59]

; #define LAS __attribute__((address_space(3)))
; __device__ __forceinline__ void hgrn_scan(const Params& p, LAS unsigned char* lds, int chain) {
;     ...
; #pragma unroll
;         for (int blk = 0; blk < 8; ++blk) {
;             const f32x4 d4 = *(const LAS f32x4*)(bb + SB_D + (16 * blk + 4 * g) * 4);
;             f32x4 s = S[blk] * d4;
; #pragma unroll
;             for (int sp = 0; sp < 2; ++sp) {
;                 const LAS unsigned char* kp = bb + SB_KD + (16 * blk + li) * HPK + (32 * sp + 4 * g) * 2;
;                 s = __builtin_amdgcn_mfma_f32_16x16x32_bf16(cat8u(*(const LAS u32x2*)kp, *(const LAS u32x2*)(kp + 32)), vf[sp], s, 0, 0, 0);
;             }
;             S[blk] = s;
;         }
.LBB0_426:
	v_add_u32_e32 v165, v153, v144
	v_add_u32_e32 v174, 0x1d200, v235
	ds_read_b64 v[204:205], v174
	ds_read_b64 v[180:181], v165 offset:0
	ds_read_b64 v[182:183], v165 offset:32
	ds_read_b64 v[184:185], v165 offset:64
	ds_read_b64 v[186:187], v165 offset:96
	ds_read_b64 v[188:189], v165 offset:2176
	ds_read_b64 v[190:191], v165 offset:2208
	ds_read_b64 v[192:193], v165 offset:2240
	ds_read_b64 v[194:195], v165 offset:2272
	s_waitcnt lgkmcnt(8)
	ds_read_b64 v[196:197], v165 offset:4352
	ds_read_b64 v[198:199], v165 offset:4384
	ds_read_b64 v[200:201], v165 offset:4416
	ds_read_b64 v[202:203], v165 offset:4448
	s_waitcnt lgkmcnt(4)
	v_mul_f32_dpp v76, v204, v76 row_newbcast:0 row_mask:0xf bank_mask:0xf
	v_mul_f32_dpp v77, v205, v77 row_newbcast:0 row_mask:0xf bank_mask:0xf
	v_mul_f32_dpp v78, v204, v78 row_newbcast:1 row_mask:0xf bank_mask:0xf
	v_mul_f32_dpp v79, v205, v79 row_newbcast:1 row_mask:0xf bank_mask:0xf
	v_mul_f32_dpp v92, v204, v92 row_newbcast:2 row_mask:0xf bank_mask:0xf
	v_mul_f32_dpp v93, v205, v93 row_newbcast:2 row_mask:0xf bank_mask:0xf
	v_mul_f32_dpp v94, v204, v94 row_newbcast:3 row_mask:0xf bank_mask:0xf
	v_mul_f32_dpp v95, v205, v95 row_newbcast:3 row_mask:0xf bank_mask:0xf
	v_mfma_f32_16x16x32_bf16 v[76:79], v[180:183], v[100:103], v[76:79]
	s_nop 0
	v_mfma_f32_16x16x32_bf16 v[92:95], v[188:191], v[100:103], v[92:95]
	v_mfma_f32_16x16x32_bf16 v[76:79], v[184:187], v[96:99], v[76:79]
	v_mfma_f32_16x16x32_bf16 v[92:95], v[192:195], v[96:99], v[92:95]
	ds_read_b64 v[180:181], v165 offset:6528
	ds_read_b64 v[182:183], v165 offset:6560
	ds_read_b64 v[184:185], v165 offset:6592
	ds_read_b64 v[186:187], v165 offset:6624
	ds_read_b64 v[188:189], v165 offset:8704
	ds_read_b64 v[190:191], v165 offset:8736
	ds_read_b64 v[192:193], v165 offset:8768
	ds_read_b64 v[194:195], v165 offset:8800
	s_waitcnt lgkmcnt(4)
	v_mul_f32_dpp v80, v204, v80 row_newbcast:4 row_mask:0xf bank_mask:0xf
	v_mul_f32_dpp v81, v205, v81 row_newbcast:4 row_mask:0xf bank_mask:0xf
	v_mul_f32_dpp v82, v204, v82 row_newbcast:5 row_mask:0xf bank_mask:0xf
	v_mul_f32_dpp v83, v205, v83 row_newbcast:5 row_mask:0xf bank_mask:0xf
	v_mul_f32_dpp v88, v204, v88 row_newbcast:6 row_mask:0xf bank_mask:0xf
	v_mul_f32_dpp v89, v205, v89 row_newbcast:6 row_mask:0xf bank_mask:0xf
	v_mul_f32_dpp v90, v204, v90 row_newbcast:7 row_mask:0xf bank_mask:0xf
	v_mul_f32_dpp v91, v205, v91 row_newbcast:7 row_mask:0xf bank_mask:0xf
	v_mfma_f32_16x16x32_bf16 v[80:83], v[196:199], v[100:103], v[80:83]
	s_nop 0
	v_mfma_f32_16x16x32_bf16 v[88:91], v[180:183], v[100:103], v[88:91]
	v_mfma_f32_16x16x32_bf16 v[80:83], v[200:203], v[96:99], v[80:83]
	v_mfma_f32_16x16x32_bf16 v[88:91], v[184:187], v[96:99], v[88:91]
	ds_read_b64 v[196:197], v165 offset:10880
	ds_read_b64 v[198:199], v165 offset:10912
	ds_read_b64 v[200:201], v165 offset:10944
	ds_read_b64 v[202:203], v165 offset:10976
	ds_read_b64 v[180:181], v165 offset:13056
	ds_read_b64 v[182:183], v165 offset:13088
	ds_read_b64 v[184:185], v165 offset:13120
	ds_read_b64 v[186:187], v165 offset:13152
	s_waitcnt lgkmcnt(4)
	v_mul_f32_dpp v72, v204, v72 row_newbcast:8 row_mask:0xf bank_mask:0xf
	v_mul_f32_dpp v73, v205, v73 row_newbcast:8 row_mask:0xf bank_mask:0xf
	v_mul_f32_dpp v74, v204, v74 row_newbcast:9 row_mask:0xf bank_mask:0xf
	v_mul_f32_dpp v75, v205, v75 row_newbcast:9 row_mask:0xf bank_mask:0xf
	v_mul_f32_dpp v84, v204, v84 row_newbcast:10 row_mask:0xf bank_mask:0xf
	v_mul_f32_dpp v85, v205, v85 row_newbcast:10 row_mask:0xf bank_mask:0xf
	v_mul_f32_dpp v86, v204, v86 row_newbcast:11 row_mask:0xf bank_mask:0xf
	v_mul_f32_dpp v87, v205, v87 row_newbcast:11 row_mask:0xf bank_mask:0xf
	v_mfma_f32_16x16x32_bf16 v[72:75], v[188:191], v[100:103], v[72:75]
	s_nop 0
	v_mfma_f32_16x16x32_bf16 v[84:87], v[196:199], v[100:103], v[84:87]
	v_mfma_f32_16x16x32_bf16 v[72:75], v[192:195], v[96:99], v[72:75]
	v_mfma_f32_16x16x32_bf16 v[84:87], v[200:203], v[96:99], v[84:87]
	ds_read_b64 v[188:189], v165 offset:15232
	ds_read_b64 v[190:191], v165 offset:15264
	ds_read_b64 v[192:193], v165 offset:15296
	ds_read_b64 v[194:195], v165 offset:15328
	s_waitcnt lgkmcnt(0)
	v_mul_f32_dpp v64, v204, v64 row_newbcast:12 row_mask:0xf bank_mask:0xf
	v_mul_f32_dpp v65, v205, v65 row_newbcast:12 row_mask:0xf bank_mask:0xf
	v_mul_f32_dpp v66, v204, v66 row_newbcast:13 row_mask:0xf bank_mask:0xf
	v_mul_f32_dpp v67, v205, v67 row_newbcast:13 row_mask:0xf bank_mask:0xf
	v_mul_f32_dpp v68, v204, v68 row_newbcast:14 row_mask:0xf bank_mask:0xf
	v_mul_f32_dpp v69, v205, v69 row_newbcast:14 row_mask:0xf bank_mask:0xf
	v_mul_f32_dpp v70, v204, v70 row_newbcast:15 row_mask:0xf bank_mask:0xf
	v_mul_f32_dpp v71, v205, v71 row_newbcast:15 row_mask:0xf bank_mask:0xf
	v_mfma_f32_16x16x32_bf16 v[64:67], v[180:183], v[100:103], v[64:67]
	s_nop 0
	v_mfma_f32_16x16x32_bf16 v[68:71], v[188:191], v[100:103], v[68:71]
	v_mfma_f32_16x16x32_bf16 v[64:67], v[184:187], v[96:99], v[64:67]
	v_mfma_f32_16x16x32_bf16 v[68:71], v[192:195], v[96:99], v[68:71]
	s_add_i32 s12, s30, 3
	s_cmp_gt_u32 s12, 34
	s_cbranch_scc1 .LBB0_432
	s_cmp_eq_u32 s14, 0
	s_cbranch_scc1 .LBB0_429
	v_add_u32_e32 v96, v154, v113
	ds_write_b128 v96, v[48:51]
	ds_write_b128 v96, v[52:55] offset:10240
	ds_write_b128 v164, v[60:63] offset:40960
